# attention units handed out by a global atomic ticket counter (one-unit lookahead) instead of static round-robin, on top of relaxed GEMM first-iteration waits
# baseline (speedup 1.0000x reference)
; #define LAS __attribute__((address_space(3)))
; __device__ __forceinline__ void attn_phase(LAS unsigned char* lds, const bf16_t* __restrict__ QKV, bf16_t* __restrict__ O, int vcu, int G) {
;     int tid = threadIdx.x; asm volatile("" : "+v"(tid)); const int lane = tid & 63, w = __builtin_amdgcn_readfirstlane(tid >> 6), l15 = lane & 15, quad = lane >> 4;
;     const int tl = 16 * w + l15;
;     bf16x8 U1, T0, T1;
; #pragma unroll
;     for (int i = 0; i < 8; ++i) { const int jj = 8 * quad + i; U1[i] = (short)0x3F80; T0[i] = (jj > l15) ? (short)0x3F80 : (short)0; T1[i] = (jj - 16 > l15) ? (short)0x3F80 : (short)0; }
;     const int cgi = tid & 15, rg = tid >> 4;
;     LAS int* flag = (LAS int*)(lds + AT_FLAG);
;     for (int u = vcu; u < 2048; u += G) {
;         const int bh = u >> 5, qb = u & 31, b = bh >> 4, h = bh & 15;
;         const size_t rowbase = (size_t)b * SEQ;
;         const bf16_t* kbase = QKV + (rowbase + 4 * rg) * NQKV + 2048 + h * 128 + 8 * cgi;
;         u32x4 kr[4], vr[4];
;         { const bf16_t* kp = kbase + (size_t)qb * 128 * NQKV;
.LBB0_974:
	s_or_b64 exec, exec, s[0:1]
	v_mov_b32_e32 v8, v204
	s_waitcnt lgkmcnt(0)
	s_barrier
	s_cmpk_lt_i32 s80, 0x800
	s_nop 0
	v_readfirstlane_b32 s2, v8
	s_cbranch_scc0 .LBB0_1025
	v_writelane_b32 v247, s56, 30
	v_and_b32_e32 v9, 15, v8
	v_bfe_u32 v12, v8, 4, 2
	v_writelane_b32 v247, s57, 31
	v_writelane_b32 v247, s60, 28
	v_lshlrev_b32_e32 v158, 3, v12
	v_or_b32_e32 v3, 16, v9
	v_writelane_b32 v247, s61, 29
	v_writelane_b32 v247, s58, 8
	s_load_dwordx2 s[4:5], s[58:59], 0x98
	v_mov_b32_e32 v4, 0x3f80
	v_writelane_b32 v247, s59, 9
	v_cmp_gt_u32_e32 vcc, v158, v3
	v_or_b32_e32 v6, 3, v158
	s_waitcnt lgkmcnt(0)
	s_add_u32 s0, s4, 0x21083a00
	s_addc_u32 s1, s5, 0
	v_mov_b32_e32 v250, s0
	v_mov_b32_e32 v251, s1
	v_mov_b32_e32 v249, 1
	s_add_u32 s0, s4, 0x11080000
	s_addc_u32 s1, s5, 0
	s_add_u32 s4, s4, 0xd080000
	s_addc_u32 s5, s5, 0
	v_writelane_b32 v247, s4, 14
	v_cndmask_b32_e32 v0, 0, v4, vcc
	v_cmp_lt_u32_e32 vcc, v158, v3
	v_writelane_b32 v247, s5, 15
	s_ashr_i32 s4, s2, 2
	v_bfi_b32 v156, -16, s4, v8
	v_cndmask_b32_e64 v1, v4, 0, vcc
	s_mov_b32 s4, 0x5040100
	v_perm_b32 v0, v1, v0, s4
	v_or_b32_e32 v1, 2, v158
	v_cmp_gt_u32_e32 vcc, v158, v9
	v_or_b32_e32 v2, 4, v158
	v_or_b32_e32 v16, 5, v158
	v_cndmask_b32_e32 v7, 0, v4, vcc
	v_cmp_lt_u32_e32 vcc, v9, v1
	v_or_b32_e32 v5, 7, v158
	v_ashrrev_i32_e32 v18, 4, v8
	v_cndmask_b32_e32 v13, 0, v4, vcc
	v_cmp_lt_u32_e32 vcc, v158, v9
	v_lshlrev_b32_e32 v20, 3, v18
	v_and_b32_e32 v20, 8, v20
	v_cndmask_b32_e64 v14, v4, 0, vcc
	v_cmp_gt_u32_e32 vcc, v6, v3
	s_movk_i32 s5, 0x110
	v_mad_u32_u24 v172, v9, s5, 0
	v_cndmask_b32_e32 v10, 0, v4, vcc
	v_cmp_gt_u32_e32 vcc, v1, v3
	v_or_b32_e32 v25, 4, v12
	v_lshlrev_b32_e32 v159, 4, v12
	v_cndmask_b32_e32 v1, 0, v4, vcc
	v_cmp_gt_u32_e32 vcc, v6, v9
	v_perm_b32 v1, v10, v1, s4
	v_or_b32_e32 v10, 6, v158
	v_cndmask_b32_e32 v15, 0, v4, vcc
	v_cmp_gt_u32_e32 vcc, v2, v9
	v_lshrrev_b32_e32 v11, 4, v8
	v_cmp_eq_u32_e64 s[6:7], 0, v8
	v_cndmask_b32_e32 v6, 0, v4, vcc
	v_cmp_gt_u32_e32 vcc, v2, v3
	s_ashr_i32 s81, s2, 7
	v_lshlrev_b32_e32 v160, 2, v18
	v_cndmask_b32_e32 v2, 0, v4, vcc
	v_cmp_gt_u32_e32 vcc, v16, v3
	v_mov_b32_e32 v163, 0
	v_lshl_add_u32 v19, v9, 4, 0
	v_cndmask_b32_e32 v17, 0, v4, vcc
	v_cmp_gt_u32_e32 vcc, v10, v3
	v_perm_b32 v2, v17, v2, s4
	s_mov_b32 s85, 0
	v_cndmask_b32_e32 v17, 0, v4, vcc
	v_cmp_gt_u32_e32 vcc, v5, v3
	v_ashrrev_i32_e32 v161, 31, v160
	v_ashrrev_i32_e32 v157, 31, v156
	v_cndmask_b32_e32 v3, 0, v4, vcc
	v_cmp_gt_u32_e32 vcc, v10, v9
	v_perm_b32 v3, v3, v17, s4
	v_lshlrev_b32_e32 v10, 3, v9
	v_cndmask_b32_e32 v17, 0, v4, vcc
	v_cmp_gt_u32_e32 vcc, v16, v9
	v_add_u32_e32 v173, v172, v159
	s_movk_i32 s89, 0x3000
	v_cndmask_b32_e32 v16, 0, v4, vcc
	v_cmp_gt_u32_e32 vcc, v5, v9
	v_perm_b32 v6, v16, v6, s4
	v_mul_u32_u24_e32 v9, 0x880, v9
	v_cndmask_b32_e32 v5, 0, v4, vcc
	v_ashrrev_i32_e32 v4, 5, v8
	v_bitop3_b32 v4, v4, v8, 15 bitop3:0x78
	v_lshlrev_b32_e32 v4, 4, v4
	v_add3_u32 v20, 0, v4, v20
	v_mul_lo_u32 v4, v156, s5
	s_add_i32 s5, 0, 0x11000
	v_add_u32_e32 v174, s5, v4
	v_perm_b32 v4, v14, v7, s4
	v_perm_b32 v7, v5, v17, s4
	v_perm_b32 v5, v15, v13, s4
	v_lshlrev_b32_e32 v13, 2, v12
	v_or_b32_e32 v14, 1, v13
	v_cmp_lt_i32_e64 s[10:11], v14, v156
	v_or_b32_e32 v14, 2, v13
	v_cmp_lt_i32_e64 s[12:13], v14, v156
	v_or_b32_e32 v14, 3, v13
	v_cmp_lt_i32_e64 s[14:15], v14, v156
	v_or_b32_e32 v14, 16, v13
	v_cmp_lt_i32_e64 s[16:17], v14, v156
	v_or_b32_e32 v14, 17, v13
	v_cmp_lt_i32_e64 s[18:19], v14, v156
	v_or_b32_e32 v14, 18, v13
	v_cmp_lt_i32_e64 s[20:21], v14, v156
	v_or_b32_e32 v14, 19, v13
	v_cmp_lt_i32_e64 s[22:23], v14, v156
	v_or_b32_e32 v14, 32, v13
	v_cmp_lt_i32_e64 s[24:25], v14, v156
	v_or_b32_e32 v14, 33, v13
	v_cmp_lt_i32_e64 s[26:27], v14, v156
	v_or_b32_e32 v14, 34, v13
	v_cmp_lt_i32_e64 s[28:29], v14, v156
	v_or_b32_e32 v14, 35, v13
	v_cmp_lt_i32_e64 s[30:31], v14, v156
	v_or_b32_e32 v14, 48, v13
	v_cmp_lt_i32_e64 s[34:35], v14, v156
	v_or_b32_e32 v14, 49, v13
	v_cmp_lt_i32_e64 s[36:37], v14, v156
	v_or_b32_e32 v14, 50, v13
	v_cmp_lt_i32_e64 s[38:39], v14, v156
	v_or_b32_e32 v14, 51, v13
	v_cmp_lt_i32_e64 s[40:41], v14, v156
	v_or_b32_e32 v14, 64, v13
	v_cmp_lt_i32_e64 s[42:43], v14, v156
	v_or_b32_e32 v14, 0x41, v13
	v_cmp_lt_i32_e64 s[44:45], v14, v156
	v_or_b32_e32 v14, 0x42, v13
	v_cmp_lt_i32_e64 s[46:47], v14, v156
	v_or_b32_e32 v14, 0x43, v13
	v_cmp_lt_i32_e64 s[48:49], v14, v156
	v_or_b32_e32 v14, 0x50, v13
	v_cmp_lt_i32_e64 s[50:51], v14, v156
	v_or_b32_e32 v14, 0x51, v13
	v_cmp_lt_i32_e64 s[52:53], v14, v156
	v_or_b32_e32 v14, 0x52, v13
	v_cmp_lt_i32_e64 s[54:55], v14, v156
	v_or_b32_e32 v14, 0x53, v13
	v_cmp_lt_i32_e64 s[56:57], v14, v156
	v_or_b32_e32 v14, 0x60, v13
	v_cmp_lt_i32_e64 s[58:59], v14, v156
	v_or_b32_e32 v14, 0x61, v13
	v_cmp_lt_i32_e64 s[60:61], v14, v156
	v_or_b32_e32 v14, 0x62, v13
	v_cmp_lt_i32_e64 s[62:63], v14, v156
	v_or_b32_e32 v14, 0x63, v13
	v_cmp_lt_i32_e64 s[64:65], v14, v156
	v_or_b32_e32 v14, 0x70, v13
	v_cmp_lt_i32_e64 s[66:67], v14, v156
	v_or_b32_e32 v14, 0x71, v13
	v_cmp_lt_i32_e64 s[68:69], v14, v156
	v_or_b32_e32 v14, 0x72, v13
	v_cmp_lt_i32_e64 s[70:71], v14, v156
	v_or_b32_e32 v14, 0x73, v13
	v_cmp_lt_i32_e64 s[72:73], v14, v156
	v_bfe_u32 v14, v8, 3, 1
	v_bitop3_b32 v26, v12, v14, 4 bitop3:0x36
	v_lshlrev_b32_e32 v175, 4, v26
	v_bitop3_b32 v26, v14, v25, 2 bitop3:0x36
	v_lshlrev_b32_e32 v176, 4, v26
	v_bitop3_b32 v26, v14, v12, 4 bitop3:0x14
	v_lshlrev_b32_e32 v177, 4, v26
	v_bitop3_b32 v26, v14, v25, 6 bitop3:0x36
	v_lshlrev_b32_e32 v178, 4, v26
	v_bitop3_b32 v26, v14, v25, 8 bitop3:0x36
	v_lshlrev_b32_e32 v179, 4, v26
	v_bitop3_b32 v26, v14, v25, 10 bitop3:0x36
; #define LAS __attribute__((address_space(3)))
; __device__ __forceinline__ void attn_phase(LAS unsigned char* lds, const bf16_t* __restrict__ QKV, bf16_t* __restrict__ O, int vcu, int G) {
;     int tid = threadIdx.x; asm volatile("" : "+v"(tid)); const int lane = tid & 63, w = __builtin_amdgcn_readfirstlane(tid >> 6), l15 = lane & 15, quad = lane >> 4;
;     const int tl = 16 * w + l15;
;     bf16x8 U1, T0, T1;
; #pragma unroll
;     for (int i = 0; i < 8; ++i) { const int jj = 8 * quad + i; U1[i] = (short)0x3F80; T0[i] = (jj > l15) ? (short)0x3F80 : (short)0; T1[i] = (jj - 16 > l15) ? (short)0x3F80 : (short)0; }
;     const int cgi = tid & 15, rg = tid >> 4;
;     LAS int* flag = (LAS int*)(lds + AT_FLAG);
	v_lshlrev_b32_e32 v180, 4, v26
	v_bitop3_b32 v26, v14, v25, 12 bitop3:0x36
	v_bitop3_b32 v25, v14, v25, 14 bitop3:0x36
	v_lshlrev_b32_e32 v181, 4, v26
	v_lshlrev_b32_e32 v182, 4, v25
	v_or_b32_e32 v25, 8, v12
	v_bitop3_b32 v26, v12, v14, 8 bitop3:0x36
	v_lshlrev_b32_e32 v183, 4, v26
	v_bitop3_b32 v26, v14, v25, 2 bitop3:0x36
	v_lshlrev_b32_e32 v184, 4, v26
	v_bitop3_b32 v26, v14, v25, 4 bitop3:0x36
	v_lshlrev_b32_e32 v185, 4, v26
	v_bitop3_b32 v26, v14, v25, 6 bitop3:0x36
	v_lshlrev_b32_e32 v186, 4, v26
	v_bitop3_b32 v26, v14, v12, 8 bitop3:0x14
	v_lshlrev_b32_e32 v187, 4, v26
	v_bitop3_b32 v26, v14, v25, 10 bitop3:0x36
	v_lshlrev_b32_e32 v188, 4, v26
	v_bitop3_b32 v26, v14, v25, 12 bitop3:0x36
	v_bitop3_b32 v25, v14, v25, 14 bitop3:0x36
	v_lshlrev_b32_e32 v189, 4, v26
	v_lshlrev_b32_e32 v190, 4, v25
	v_or_b32_e32 v25, 12, v12
	v_bitop3_b32 v26, v12, v14, 12 bitop3:0x36
	v_lshlrev_b32_e32 v191, 4, v26
	v_bitop3_b32 v26, v14, v25, 2 bitop3:0x36
	v_bitop3_b32 v15, v14, v12, 2 bitop3:0x36
	v_bitop3_b32 v16, v14, v12, 4 bitop3:0x36
	v_bitop3_b32 v17, v14, v12, 6 bitop3:0x36
	v_bitop3_b32 v21, v14, v12, 8 bitop3:0x36
	v_bitop3_b32 v22, v14, v12, 10 bitop3:0x36
	v_bitop3_b32 v23, v14, v12, 12 bitop3:0x36
	v_bitop3_b32 v24, v14, v12, 14 bitop3:0x36
	v_lshlrev_b32_e32 v192, 4, v26
	v_bitop3_b32 v26, v14, v25, 4 bitop3:0x36
	v_bitop3_b32 v12, v14, v12, 12 bitop3:0x14
	v_lshlrev_b32_e32 v193, 4, v26
	v_bitop3_b32 v26, v14, v25, 6 bitop3:0x36
	v_lshlrev_b32_e32 v197, 4, v12
	v_bitop3_b32 v12, v14, v25, 14 bitop3:0x36
	v_and_b32_e32 v8, 16, v8
	s_cmpk_gt_u32 s2, 0x7f
	v_bitop3_b32 v11, v14, v11, 3 bitop3:0x78
	v_lshlrev_b32_e32 v194, 4, v26
	v_bitop3_b32 v26, v14, v25, 8 bitop3:0x36
	v_lshlrev_b32_e32 v198, 4, v12
	v_add_u32_e32 v12, 12, v13
	v_cmp_eq_u32_e64 s[74:75], 0, v8
	s_movk_i32 s2, 0x440
	s_cselect_b64 s[86:87], -1, 0
	v_lshlrev_b32_e32 v11, 4, v11
	v_lshlrev_b32_e32 v15, 4, v15
	v_lshlrev_b32_e32 v16, 4, v16
	v_lshlrev_b32_e32 v17, 4, v17
	v_lshlrev_b32_e32 v21, 4, v21
	v_lshlrev_b32_e32 v22, 4, v22
	v_lshlrev_b32_e32 v23, 4, v23
	v_lshlrev_b32_e32 v24, 4, v24
	v_lshlrev_b32_e32 v195, 4, v26
	v_bitop3_b32 v26, v14, v25, 10 bitop3:0x36
	v_cndmask_b32_e64 v8, v12, v13, s[74:75]
	v_mul_lo_u32 v12, v18, s2
	s_add_i32 s2, 0, 0x19800
	v_cmp_lt_i32_e64 s[8:9], v13, v156
	v_lshlrev_b32_e32 v196, 4, v26
	v_lshlrev_b32_e32 v162, 1, v10
	v_lshlrev_b32_e32 v164, 1, v158
	v_writelane_b32 v247, s2, 16
	v_add_u32_e32 v199, v19, v12
	s_mov_b32 s97, 0xffff
	v_add_u32_e32 v200, v20, v9
	s_mov_b32 s4, 0xffff0000
	s_mov_b32 s88, 0x3e0293ee
	s_mov_b32 s5, 0x42800000
	v_add_u32_e32 v201, v172, v11
	v_mov_b32_e32 v202, 1
	v_lshlrev_b32_e32 v166, 1, v8
	v_mov_b32_e32 v224, v163
	v_mov_b32_e32 v225, v163
	v_mov_b32_e32 v203, 0x180000
	v_mbcnt_hi_u32_b32 v206, -1, v205
	v_add_u32_e32 v207, v172, v15
	v_add_u32_e32 v208, v172, v16
	v_add_u32_e32 v209, v172, v17
	v_add_u32_e32 v210, v172, v21
	v_add_u32_e32 v211, v172, v22
	v_add_u32_e32 v212, v172, v23
	v_add_u32_e32 v213, v172, v24
	s_mov_b32 s2, s80
	s_mov_b32 s76, 0x3f803f80
	s_branch .LBB0_977
; __device__ __forceinline__ unsigned pk2(float lo, float hi) { return pg8::cvt_pk_bf16(lo, hi); }
; __device__ __forceinline__ void attn_phase(LAS unsigned char* lds, const bf16_t* __restrict__ QKV, bf16_t* __restrict__ O, int vcu, int G) {
;     ...
;     for (int u = vcu; u < 2048; u += G) {
;         const int bh = u >> 5, qb = u & 31, b = bh >> 4, h = bh & 15;
;         const size_t rowbase = (size_t)b * SEQ;
;         const bf16_t* kbase = QKV + (rowbase + 4 * rg) * NQKV + 2048 + h * 128 + 8 * cgi;
;         u32x4 kr[4], vr[4];
;         { const bf16_t* kp = kbase + (size_t)qb * 128 * NQKV;
; #pragma unroll
;           for (int i = 0; i < 4; ++i) { kr[i] = *(const u32x4*)(kp + (size_t)i * NQKV); vr[i] = *(const u32x4*)(kp + (size_t)i * NQKV + 2048); } }
;         bf16x8 qf[4];
;         { const bf16_t* qp = QKV + (rowbase + qb * 128 + tl) * NQKV + h * 128 + quad * 8;
; #pragma unroll
;           for (int ks = 0; ks < 4; ++ks) qf[ks] = *(const bf16x8*)(qp + 32 * ks); }
;         f32x4 accO[8];
; #pragma unroll
;         for (int et = 0; et < 8; ++et) accO[et] = (f32x4){0.f, 0.f, 0.f, 0.f};
;         float R = 0.f;
;         if (tid == 0) { flag[0] = 0; flag[1] = 0; }
;     ...
;         { bf16_t* op = O + (rowbase + qb * 128 + tl) * DM + h * 128;
; #pragma unroll
;           for (int a = 0; a < 4; ++a) { u32x2 X, Y; X.x = pk2(accO[2 * a][0], accO[2 * a][1]); X.y = pk2(accO[2 * a][2], accO[2 * a][3]); Y.x = pk2(accO[2 * a + 1][0], accO[2 * a + 1][1]); Y.y = pk2(accO[2 * a + 1][2], accO[2 * a + 1][3]);
;               u32x4 o; const int e0 = pair16(X, Y, quad, o); *(u32x4*)(op + 32 * a + e0) = o; } }
.LBB0_976:
	v_mov_b32_e32 v252, 0x1a000
	ds_read_b32 v252, v252
	s_waitcnt lgkmcnt(0)
	v_readfirstlane_b32 s80, v252
	s_nop 3
	s_add_i32 s80, s80, s33
	s_mov_b32 s2, s80
	v_readlane_b32 s78, v247, 14
	s_waitcnt vmcnt(7)
	v_and_b32_e32 v11, 64, v206
	v_lshlrev_b64 v[8:9], 12, v[170:171]
	v_readlane_b32 s79, v247, 15
	v_xor_b32_e32 v10, 16, v206
	v_add_u32_e32 v11, 64, v11
	v_lshl_add_u64 v[8:9], s[78:79], 0, v[8:9]
	v_cmp_lt_i32_e32 vcc, v10, v11
	v_lshl_add_u64 v[8:9], v[8:9], 0, s[84:85]
	v_mov_b32_e32 v167, v163
	v_cndmask_b32_e32 v10, v206, v10, vcc
	s_waitcnt vmcnt(6)
	v_lshlrev_b32_e32 v14, 2, v10
	v_lshl_add_u64 v[12:13], v[8:9], 0, v[166:167]
	v_cvt_pk_bf16_f32 v8, v96, v97
	v_cvt_pk_bf16_f32 v9, v98, v99
	v_cvt_pk_bf16_f32 v10, v108, v109
	v_cvt_pk_bf16_f32 v11, v110, v111
	v_cndmask_b32_e64 v15, v9, v11, s[74:75]
	s_waitcnt vmcnt(5)
	v_cndmask_b32_e64 v16, v8, v10, s[74:75]
	ds_bpermute_b32 v16, v14, v16
	ds_bpermute_b32 v15, v14, v15
	s_cmpk_lt_i32 s80, 0x800
	s_waitcnt lgkmcnt(1)
	v_cndmask_b32_e64 v10, v10, v16, s[74:75]
	s_waitcnt lgkmcnt(0)
	v_cndmask_b32_e64 v11, v11, v15, s[74:75]
	v_cndmask_b32_e64 v9, v15, v9, s[74:75]
	v_cndmask_b32_e64 v8, v16, v8, s[74:75]
	global_store_dwordx4 v[12:13], v[8:11], off
	s_nop 1
	v_cvt_pk_bf16_f32 v8, v100, v101
	v_cvt_pk_bf16_f32 v9, v102, v103
	v_cvt_pk_bf16_f32 v10, v116, v117
	v_cvt_pk_bf16_f32 v11, v118, v119
	v_cndmask_b32_e64 v15, v9, v11, s[74:75]
	v_cndmask_b32_e64 v16, v8, v10, s[74:75]
	ds_bpermute_b32 v16, v14, v16
	ds_bpermute_b32 v15, v14, v15
	s_waitcnt lgkmcnt(1)
	v_cndmask_b32_e64 v10, v10, v16, s[74:75]
	s_waitcnt lgkmcnt(0)
	v_cndmask_b32_e64 v11, v11, v15, s[74:75]
	v_cndmask_b32_e64 v9, v15, v9, s[74:75]
	v_cndmask_b32_e64 v8, v16, v8, s[74:75]
	global_store_dwordx4 v[12:13], v[8:11], off offset:64
	s_nop 1
	v_cvt_pk_bf16_f32 v8, v104, v105
	v_cvt_pk_bf16_f32 v9, v106, v107
	v_cvt_pk_bf16_f32 v10, v120, v121
	v_cvt_pk_bf16_f32 v11, v122, v123
	v_cndmask_b32_e64 v15, v9, v11, s[74:75]
	v_cndmask_b32_e64 v16, v8, v10, s[74:75]
	ds_bpermute_b32 v16, v14, v16
	ds_bpermute_b32 v15, v14, v15
	s_waitcnt lgkmcnt(1)
	v_cndmask_b32_e64 v10, v10, v16, s[74:75]
	s_waitcnt lgkmcnt(0)
	v_cndmask_b32_e64 v11, v11, v15, s[74:75]
	v_cndmask_b32_e64 v9, v15, v9, s[74:75]
	v_cndmask_b32_e64 v8, v16, v8, s[74:75]
	global_store_dwordx4 v[12:13], v[8:11], off offset:128
	s_nop 1
	v_cvt_pk_bf16_f32 v8, v112, v113
	v_cvt_pk_bf16_f32 v9, v114, v115
	v_cvt_pk_bf16_f32 v10, v124, v125
	v_cvt_pk_bf16_f32 v11, v126, v127
	v_cndmask_b32_e64 v15, v9, v11, s[74:75]
	v_cndmask_b32_e64 v16, v8, v10, s[74:75]
	ds_bpermute_b32 v16, v14, v16
	ds_bpermute_b32 v14, v14, v15
	s_waitcnt lgkmcnt(1)
	v_cndmask_b32_e64 v10, v10, v16, s[74:75]
	s_waitcnt lgkmcnt(0)
	v_cndmask_b32_e64 v11, v11, v14, s[74:75]
	v_cndmask_b32_e64 v9, v14, v9, s[74:75]
	v_cndmask_b32_e64 v8, v16, v8, s[74:75]
	global_store_dwordx4 v[12:13], v[8:11], off offset:192
	s_cbranch_scc0 .LBB0_1024
.LBB0_977:
	s_ashr_i32 s78, s80, 9
	s_ashr_i32 s79, s78, 31
	s_lshl_b64 s[78:79], s[78:79], 12
	v_lshl_add_u64 v[8:9], s[78:79], 0, v[160:161]
	s_waitcnt vmcnt(7)
	v_mov_b64_e32 v[24:25], s[0:1]
	s_lshl_b32 s83, s80, 2
	v_mad_u64_u32 v[10:11], s[90:91], v8, s89, v[24:25]
	s_and_b32 s83, s83, 0x780
	v_mad_i32_i24 v11, v9, s89, v11
	s_lshl_b32 s84, s83, 1
	v_lshl_add_u64 v[8:9], v[10:11], 0, s[84:85]
	s_and_b32 s77, s80, 31
	v_lshl_add_u64 v[8:9], v[8:9], 0, v[162:163]
	s_mov_b64 s[90:91], 0x1000
	v_lshl_add_u64 v[168:169], v[8:9], 0, s[90:91]
	s_mul_i32 s90, s77, 0x180000
	s_mov_b32 s91, s85
	v_lshl_add_u64 v[26:27], v[168:169], 0, s[90:91]
	s_movk_i32 s83, 0x1000
	v_add_co_u32_e32 v12, vcc, s83, v26
	s_movk_i32 s83, 0x4000
	s_nop 0
	v_addc_co_u32_e32 v13, vcc, 0, v27, vcc
	s_lshl_b32 s77, s77, 7
	v_add_co_u32_e32 v20, vcc, s83, v26
	s_or_b32 s78, s78, s77
	s_nop 0
	v_addc_co_u32_e32 v21, vcc, 0, v27, vcc
	s_movk_i32 s83, 0x7000
	v_lshl_add_u64 v[170:171], s[78:79], 0, v[156:157]
	s_waitcnt vmcnt(6)
	v_add_co_u32_e32 v28, vcc, s83, v26
	v_mad_u64_u32 v[24:25], s[78:79], v170, s89, v[24:25]
	s_nop 0
	v_addc_co_u32_e32 v29, vcc, 0, v27, vcc
	s_mov_b32 s83, 0xa000
	v_mad_i32_i24 v25, v171, s89, v25
	global_load_dwordx4 v[8:11], v[26:27], off
	s_nop 0
	global_load_dwordx4 v[12:15], v[12:13], off
	v_add_co_u32_e32 v26, vcc, s83, v26
	v_lshl_add_u64 v[24:25], v[24:25], 0, s[84:85]
	v_mov_b32_e32 v165, v163
	v_addc_co_u32_e32 v27, vcc, 0, v27, vcc
	s_waitcnt vmcnt(6)
	v_lshl_add_u64 v[36:37], v[24:25], 0, v[164:165]
	global_load_dwordx4 v[16:19], v[20:21], off offset:-4096
	s_nop 0
	global_load_dwordx4 v[20:23], v[20:21], off
	s_nop 0
	global_load_dwordx4 v[40:43], v[28:29], off offset:-4096
	global_load_dwordx4 v[44:47], v[28:29], off
	global_load_dwordx4 v[48:51], v[26:27], off offset:-4096
	global_load_dwordx4 v[52:55], v[26:27], off
	s_nop 0
	global_load_dwordx4 v[24:27], v[36:37], off
	global_load_dwordx4 v[28:31], v[36:37], off offset:64
	global_load_dwordx4 v[32:35], v[36:37], off offset:128
	s_nop 0
	global_load_dwordx4 v[36:39], v[36:37], off offset:192
	s_and_saveexec_b64 s[78:79], s[6:7]
	s_cbranch_execz .LBB0_979
	v_readlane_b32 s77, v247, 16
	s_waitcnt vmcnt(13)
	s_nop 0
	v_mov_b32_e32 v56, s77
	ds_write_b64 v56, v[224:225]
	global_atomic_add v248, v[250:251], v249, off sc0

; #define WG_BAR() do { asm volatile("s_waitcnt lgkmcnt(0)" ::: "memory"); __builtin_amdgcn_s_barrier(); asm volatile("" ::: "memory"); } while (0)
; __device__ __forceinline__ void attn_phase(LAS unsigned char* lds, const bf16_t* __restrict__ QKV, bf16_t* __restrict__ O, int vcu, int G) {
;     ...
;             if (!(R < -134.0f)) flag[it & 1] = 1;
;             WG_BAR();
;             const int notdone = flag[it & 1];
;             if (tid == 0) flag[(it + 1) & 1] = 0;
;             if (notdone == 0) break;
.LBB0_1018:
	v_add_f32_e32 v165, v165, v214
	s_mov_b32 s77, 0xc3060000
	v_cmp_ngt_f32_e32 vcc, s77, v165
	s_and_b32 s77, s96, 1
	s_and_saveexec_b64 s[78:79], vcc
	s_lshl_b32 s90, s77, 2
	s_add_i32 s90, s90, 0
	s_add_i32 s90, s90, 0x19800
	v_mov_b32_e32 v56, s90
	ds_write_b32 v56, v202
	s_or_b64 exec, exec, s[78:79]
	s_lshl_b32 s78, s77, 2
	s_add_i32 s78, s78, 0
	s_add_i32 s78, s78, 0x19800
	s_and_saveexec_b64 s[90:91], s[6:7]
	s_cbranch_execz .Lq_skipE
	v_mov_b32_e32 v56, 0x1a000
	ds_write_b32 v56, v248
.Lq_skipE:
	s_or_b64 exec, exec, s[90:91]
	s_waitcnt lgkmcnt(0)
	s_barrier
	v_mov_b32_e32 v56, s78
	ds_read_b32 v56, v56
	s_and_saveexec_b64 s[78:79], s[6:7]
	s_cbranch_execz .LBB0_1022
	s_xor_b32 s77, s77, 1
	s_lshl_b32 s77, s77, 2
	s_add_i32 s77, s77, 0
	s_add_i32 s77, s77, 0x19800
	v_mov_b32_e32 v57, s77
	ds_write_b32 v57, v163
